# stack3 + EpiMerge non-FIRST: second-half gate/prev loads issued pairwise inside the first half (homes = dead first-half load regs)
# baseline (speedup 1.0000x reference)
; __device__ __forceinline__ u32x4 pack8(const f32x4 v0, const f32x4 v1) { u32x4 w; w.x = cvt_pk_bf16(v0[0], v0[1]); w.y = cvt_pk_bf16(v0[2], v0[3]); w.z = cvt_pk_bf16(v1[0], v1[1]); w.w = cvt_pk_bf16(v1[2], v1[3]); return w; }
;     __device__ __forceinline__ void operator()(const f32x4 (&acc)[2][2][4][2], const Unit& u, int wr, int wc, int fr_, int fq) const {
;     ...
;         const size_t row0 = (size_t)u.pm * BM + wr * 64 + fr; const int col0 = u.pn * BM + wc * 32 + 8 * fq;
; #pragma unroll
;         for (int ai = 0; ai < 2; ++ai) {
;             u32x4 gw[4][2], ow[4][2];
; #pragma unroll
;             for (int m = 0; m < 4; ++m)
; #pragma unroll
;                 for (int bj = 0; bj < 2; ++bj) { const size_t r = row0 + ai * HALF + m * 16; const int c = col0 + bj * HALF;
;                     gw[m][bj] = *(const u32x4*)(G + r * 6144 + goff + c); if (!FIRST) ow[m][bj] = *(const u32x4*)(Mo + r * DM + c); }
; #pragma unroll
;             for (int m = 0; m < 4; ++m)
; #pragma unroll
;                 for (int bj = 0; bj < 2; ++bj) { const size_t r = row0 + ai * HALF + m * 16; const int c = col0 + bj * HALF;
;                     f32x4 g0, g1; unpack8(gw[m][bj], g0, g1);
;                     f32x4 v0 = g0 * acc[ai][bj][m][0], v1 = g1 * acc[ai][bj][m][1];
;                     if (!FIRST) { f32x4 o0, o1; unpack8(ow[m][bj], o0, o1); v0 += o0; v1 += o1; }
;                     *(u32x4*)((Mdst ? Mdst : Mo) + r * DM + c) = pack8(v0, v1); }
;             asm volatile("" ::: "memory"); }
.LBB0_1143:
	s_ashr_i32 s31, s30, 31
	s_lshl_b64 s[0:1], s[30:31], 8
	v_mov_b32_e32 v130, v222
	s_add_u32 s0, s0, s73
	s_addc_u32 s1, s1, s89
	v_ashrrev_i32_e32 v131, 31, v130
	v_lshl_add_u64 v[130:131], s[0:1], 0, v[130:131]
	v_lshl_or_b32 v132, s28, 8, v224
	v_mov_b64_e32 v[134:135], s[18:19]
	s_movk_i32 s21, 0x3000
	v_ashrrev_i32_e32 v133, 31, v132
	v_mad_u64_u32 v[134:135], s[0:1], v130, s21, v[134:135]
	v_mad_i32_i24 v135, v131, s21, v135
	v_lshlrev_b64 v[132:133], 1, v[132:133]
	v_lshlrev_b64 v[130:131], 12, v[130:131]
	v_lshl_add_u64 v[206:207], v[134:135], 0, v[132:133]
	v_lshl_add_u64 v[130:131], s[2:3], 0, v[130:131]
	global_load_dwordx4 v[226:229], v[206:207], off
	v_lshl_add_u64 v[208:209], v[130:131], 0, v[132:133]
	global_load_dwordx4 v[244:247], v[208:209], off
	global_load_dwordx4 v[182:185], v[206:207], off offset:256
	global_load_dwordx4 v[178:181], v[208:209], off offset:256
	s_mov_b32 s91, 0x30000
	v_add_co_u32_e32 v132, vcc, s91, v206
	s_mov_b64 s[30:31], 0x30000
	s_nop 0
	v_addc_co_u32_e32 v133, vcc, 0, v207, vcc
	global_load_dwordx4 v[170:173], v[132:133], off
	v_add_co_u32_e32 v220, vcc, s80, v208
	v_lshl_add_u64 v[130:131], v[206:207], 0, s[30:31]
	s_nop 0
	v_addc_co_u32_e32 v221, vcc, 0, v209, vcc
	v_lshl_add_u64 v[218:219], v[208:209], 0, s[48:49]
	global_load_dwordx4 v[174:177], v[220:221], off
	global_load_dwordx4 v[166:169], v[130:131], off offset:256
	global_load_dwordx4 v[162:165], v[218:219], off offset:256
	s_mov_b32 s94, 0x60000
	v_add_co_u32_e32 v132, vcc, s94, v206
	s_mov_b64 s[0:1], 0x60000
	s_nop 0
	v_addc_co_u32_e32 v133, vcc, 0, v207, vcc
	global_load_dwordx4 v[154:157], v[132:133], off
	v_add_co_u32_e32 v216, vcc, s95, v208
	v_lshl_add_u64 v[130:131], v[206:207], 0, s[0:1]
	s_mov_b64 s[0:1], 0x20000
	v_addc_co_u32_e32 v217, vcc, 0, v209, vcc
	v_lshl_add_u64 v[214:215], v[208:209], 0, s[0:1]
	global_load_dwordx4 v[158:161], v[216:217], off
	global_load_dwordx4 v[150:153], v[130:131], off offset:256
	global_load_dwordx4 v[146:149], v[214:215], off offset:256
	s_mov_b32 s0, 0x90000
	v_add_co_u32_e32 v132, vcc, s0, v206
	s_mov_b64 s[34:35], 0x90000
	s_nop 0
	v_addc_co_u32_e32 v133, vcc, 0, v207, vcc
	global_load_dwordx4 v[138:141], v[132:133], off
	v_add_co_u32_e32 v212, vcc, s91, v208
	v_lshl_add_u64 v[130:131], v[206:207], 0, s[34:35]
	s_nop 0
	v_addc_co_u32_e32 v213, vcc, 0, v209, vcc
	v_lshl_add_u64 v[210:211], v[208:209], 0, s[30:31]
	global_load_dwordx4 v[142:145], v[212:213], off
	global_load_dwordx4 v[134:137], v[130:131], off offset:256
	s_nop 0
	global_load_dwordx4 v[130:133], v[210:211], off offset:256
	s_mov_b32 s1, 0x180000
	s_mov_b32 s52, 0x80000
	s_mov_b64 s[30:31], 0x180000
	s_waitcnt vmcnt(0)
	v_lshlrev_b32_e32 v248, 16, v246
	v_lshlrev_b32_e32 v188, 16, v226
	v_and_b32_e32 v189, 0xffff0000, v226
	v_lshlrev_b32_e32 v190, 16, v227
	v_and_b32_e32 v191, 0xffff0000, v227
	v_lshlrev_b32_e32 v192, 16, v228
	v_and_b32_e32 v193, 0xffff0000, v228
	v_lshlrev_b32_e32 v226, 16, v229
	v_and_b32_e32 v227, 0xffff0000, v229
	v_lshlrev_b32_e32 v228, 16, v244
	v_and_b32_e32 v229, 0xffff0000, v244
	v_and_b32_e32 v249, 0xffff0000, v246
	v_lshlrev_b32_e32 v246, 16, v247
	v_and_b32_e32 v247, 0xffff0000, v247
	v_lshlrev_b32_e32 v244, 16, v245
	v_and_b32_e32 v245, 0xffff0000, v245
	v_pk_fma_f32 v[126:127], v[126:127], v[188:189], v[228:229]
	v_pk_fma_f32 v[188:189], v[124:125], v[226:227], v[246:247]
	v_pk_fma_f32 v[124:125], v[122:123], v[192:193], v[248:249]
	v_pk_fma_f32 v[128:129], v[128:129], v[190:191], v[244:245]
	v_cvt_pk_bf16_f32 v122, v126, v127
	v_lshlrev_b32_e32 v126, 16, v184
	v_cvt_pk_bf16_f32 v123, v128, v129
	v_cvt_pk_bf16_f32 v124, v124, v125
	v_cvt_pk_bf16_f32 v125, v188, v189
	global_store_dwordx4 v[208:209], v[122:125], off
	v_add_co_u32_e32 v250, vcc, 0x180000, v206
	s_nop 1
	v_addc_co_u32_e32 v251, vcc, 0, v207, vcc
	v_add_co_u32_e32 v252, vcc, 0x80000, v208
	s_nop 1
	v_addc_co_u32_e32 v253, vcc, 0, v209, vcc
	global_load_dwordx4 v[226:229], v[250:251], off
	global_load_dwordx4 v[244:247], v[252:253], off
	v_and_b32_e32 v127, 0xffff0000, v184
	v_lshlrev_b32_e32 v128, 16, v185
	v_lshlrev_b32_e32 v122, 16, v182
	v_and_b32_e32 v123, 0xffff0000, v182
	v_lshlrev_b32_e32 v124, 16, v183
	v_and_b32_e32 v125, 0xffff0000, v183
	v_and_b32_e32 v129, 0xffff0000, v185
	v_lshlrev_b32_e32 v182, 16, v178
	v_and_b32_e32 v183, 0xffff0000, v178
	v_lshlrev_b32_e32 v184, 16, v180
	v_and_b32_e32 v185, 0xffff0000, v180
	v_lshlrev_b32_e32 v180, 16, v181
	v_and_b32_e32 v181, 0xffff0000, v181
	v_lshlrev_b32_e32 v178, 16, v179
	v_and_b32_e32 v179, 0xffff0000, v179
	v_pk_fma_f32 v[118:119], v[118:119], v[122:123], v[182:183]
	v_pk_fma_f32 v[122:123], v[116:117], v[128:129], v[180:181]
	v_pk_fma_f32 v[116:117], v[114:115], v[126:127], v[184:185]
	v_pk_fma_f32 v[120:121], v[120:121], v[124:125], v[178:179]
	v_cvt_pk_bf16_f32 v114, v118, v119
	v_lshlrev_b32_e32 v118, 16, v172
	v_cvt_pk_bf16_f32 v115, v120, v121
	v_cvt_pk_bf16_f32 v116, v116, v117
	v_cvt_pk_bf16_f32 v117, v122, v123
	global_store_dwordx4 v[208:209], v[114:117], off offset:256
	v_add_co_u32_e32 v250, vcc, 0x180000, v206
	s_nop 1
	v_addc_co_u32_e32 v251, vcc, 0, v207, vcc
	v_add_co_u32_e32 v252, vcc, 0x80000, v208
	s_nop 1
	v_addc_co_u32_e32 v253, vcc, 0, v209, vcc
	global_load_dwordx4 v[182:185], v[250:251], off offset:256
	global_load_dwordx4 v[178:181], v[252:253], off offset:256
	v_and_b32_e32 v119, 0xffff0000, v172
	v_lshlrev_b32_e32 v120, 16, v173
	v_lshlrev_b32_e32 v114, 16, v170
	v_and_b32_e32 v115, 0xffff0000, v170
	v_lshlrev_b32_e32 v116, 16, v171
	v_and_b32_e32 v117, 0xffff0000, v171
	v_and_b32_e32 v121, 0xffff0000, v173
	v_lshlrev_b32_e32 v122, 16, v174
; __device__ __forceinline__ u32x4 pack8(const f32x4 v0, const f32x4 v1) { u32x4 w; w.x = cvt_pk_bf16(v0[0], v0[1]); w.y = cvt_pk_bf16(v0[2], v0[3]); w.z = cvt_pk_bf16(v1[0], v1[1]); w.w = cvt_pk_bf16(v1[2], v1[3]); return w; }
;     __device__ __forceinline__ void operator()(const f32x4 (&acc)[2][2][4][2], const Unit& u, int wr, int wc, int fr_, int fq) const {
;     ...
;             for (int m = 0; m < 4; ++m)
; #pragma unroll
;                 for (int bj = 0; bj < 2; ++bj) { const size_t r = row0 + ai * HALF + m * 16; const int c = col0 + bj * HALF;
;                     f32x4 g0, g1; unpack8(gw[m][bj], g0, g1);
;                     f32x4 v0 = g0 * acc[ai][bj][m][0], v1 = g1 * acc[ai][bj][m][1];
;                     if (!FIRST) { f32x4 o0, o1; unpack8(ow[m][bj], o0, o1); v0 += o0; v1 += o1; }
;                     *(u32x4*)((Mdst ? Mdst : Mo) + r * DM + c) = pack8(v0, v1); }
;             asm volatile("" ::: "memory"); }
	v_and_b32_e32 v123, 0xffff0000, v174
	v_lshlrev_b32_e32 v124, 16, v175
	v_and_b32_e32 v125, 0xffff0000, v175
	v_lshlrev_b32_e32 v126, 16, v176
	v_and_b32_e32 v127, 0xffff0000, v176
	v_lshlrev_b32_e32 v128, 16, v177
	v_and_b32_e32 v129, 0xffff0000, v177
	v_pk_fma_f32 v[112:113], v[112:113], v[116:117], v[124:125]
	v_pk_fma_f32 v[110:111], v[110:111], v[114:115], v[122:123]
	v_pk_fma_f32 v[114:115], v[108:109], v[120:121], v[128:129]
	v_pk_fma_f32 v[108:109], v[106:107], v[118:119], v[126:127]
	v_cvt_pk_bf16_f32 v106, v110, v111
	v_cvt_pk_bf16_f32 v107, v112, v113
	v_lshlrev_b32_e32 v110, 16, v168
	v_cvt_pk_bf16_f32 v108, v108, v109
	v_cvt_pk_bf16_f32 v109, v114, v115
	global_store_dwordx4 v[220:221], v[106:109], off
	v_add_co_u32_e32 v250, vcc, 0x1b0000, v206
	s_nop 1
	v_addc_co_u32_e32 v251, vcc, 0, v207, vcc
	v_add_co_u32_e32 v252, vcc, 0x90000, v208
	s_nop 1
	v_addc_co_u32_e32 v253, vcc, 0, v209, vcc
	global_load_dwordx4 v[170:173], v[250:251], off
	global_load_dwordx4 v[174:177], v[252:253], off
	v_and_b32_e32 v111, 0xffff0000, v168
	v_lshlrev_b32_e32 v112, 16, v169
	v_lshlrev_b32_e32 v106, 16, v166
	v_and_b32_e32 v107, 0xffff0000, v166
	v_and_b32_e32 v113, 0xffff0000, v169
	v_lshlrev_b32_e32 v114, 16, v162
	v_and_b32_e32 v115, 0xffff0000, v162
	v_lshlrev_b32_e32 v118, 16, v164
	v_and_b32_e32 v119, 0xffff0000, v164
	v_lshlrev_b32_e32 v120, 16, v165
	v_and_b32_e32 v121, 0xffff0000, v165
	v_lshlrev_b32_e32 v108, 16, v167
	v_and_b32_e32 v109, 0xffff0000, v167
	v_lshlrev_b32_e32 v116, 16, v163
	v_and_b32_e32 v117, 0xffff0000, v163
	v_pk_fma_f32 v[102:103], v[102:103], v[106:107], v[114:115]
	v_pk_fma_f32 v[106:107], v[100:101], v[112:113], v[120:121]
	v_pk_fma_f32 v[100:101], v[98:99], v[110:111], v[118:119]
	v_pk_fma_f32 v[104:105], v[104:105], v[108:109], v[116:117]
	v_cvt_pk_bf16_f32 v98, v102, v103
	v_lshlrev_b32_e32 v102, 16, v156
	v_cvt_pk_bf16_f32 v99, v104, v105
	v_cvt_pk_bf16_f32 v100, v100, v101
	v_cvt_pk_bf16_f32 v101, v106, v107
	global_store_dwordx4 v[218:219], v[98:101], off offset:256
	v_add_co_u32_e32 v250, vcc, 0x1b0000, v206
	s_nop 1
	v_addc_co_u32_e32 v251, vcc, 0, v207, vcc
	v_add_co_u32_e32 v252, vcc, 0x90000, v208
	s_nop 1
	v_addc_co_u32_e32 v253, vcc, 0, v209, vcc
	global_load_dwordx4 v[166:169], v[250:251], off offset:256
	global_load_dwordx4 v[162:165], v[252:253], off offset:256
	v_and_b32_e32 v103, 0xffff0000, v156
	v_lshlrev_b32_e32 v104, 16, v157
	v_lshlrev_b32_e32 v98, 16, v154
	v_and_b32_e32 v99, 0xffff0000, v154
	v_lshlrev_b32_e32 v100, 16, v155
	v_and_b32_e32 v101, 0xffff0000, v155
	v_and_b32_e32 v105, 0xffff0000, v157
	v_lshlrev_b32_e32 v106, 16, v158
	v_and_b32_e32 v107, 0xffff0000, v158
	v_lshlrev_b32_e32 v108, 16, v159
	v_and_b32_e32 v109, 0xffff0000, v159
	v_lshlrev_b32_e32 v110, 16, v160
	v_and_b32_e32 v111, 0xffff0000, v160
	v_lshlrev_b32_e32 v112, 16, v161
	v_and_b32_e32 v113, 0xffff0000, v161
	v_pk_fma_f32 v[96:97], v[96:97], v[100:101], v[108:109]
	v_pk_fma_f32 v[94:95], v[94:95], v[98:99], v[106:107]
	v_pk_fma_f32 v[98:99], v[92:93], v[104:105], v[112:113]
	v_pk_fma_f32 v[92:93], v[90:91], v[102:103], v[110:111]
	v_cvt_pk_bf16_f32 v90, v94, v95
	v_cvt_pk_bf16_f32 v91, v96, v97
	v_lshlrev_b32_e32 v94, 16, v152
	v_cvt_pk_bf16_f32 v92, v92, v93
	v_cvt_pk_bf16_f32 v93, v98, v99
	global_store_dwordx4 v[216:217], v[90:93], off
	v_add_co_u32_e32 v250, vcc, 0x1e0000, v206
	s_nop 1
	v_addc_co_u32_e32 v251, vcc, 0, v207, vcc
	v_add_co_u32_e32 v252, vcc, 0xa0000, v208
	s_nop 1
	v_addc_co_u32_e32 v253, vcc, 0, v209, vcc
	global_load_dwordx4 v[154:157], v[250:251], off
	global_load_dwordx4 v[158:161], v[252:253], off
	v_and_b32_e32 v95, 0xffff0000, v152
	v_lshlrev_b32_e32 v96, 16, v153
	v_lshlrev_b32_e32 v90, 16, v150
	v_and_b32_e32 v91, 0xffff0000, v150
	v_and_b32_e32 v97, 0xffff0000, v153
	v_lshlrev_b32_e32 v98, 16, v146
	v_and_b32_e32 v99, 0xffff0000, v146
	v_lshlrev_b32_e32 v102, 16, v148
	v_and_b32_e32 v103, 0xffff0000, v148
	v_lshlrev_b32_e32 v104, 16, v149
	v_and_b32_e32 v105, 0xffff0000, v149
	v_lshlrev_b32_e32 v92, 16, v151
	v_and_b32_e32 v93, 0xffff0000, v151
	v_lshlrev_b32_e32 v100, 16, v147
	v_and_b32_e32 v101, 0xffff0000, v147
	v_pk_fma_f32 v[86:87], v[86:87], v[90:91], v[98:99]
	v_pk_fma_f32 v[90:91], v[84:85], v[96:97], v[104:105]
	v_pk_fma_f32 v[84:85], v[82:83], v[94:95], v[102:103]
	v_pk_fma_f32 v[88:89], v[88:89], v[92:93], v[100:101]
	v_cvt_pk_bf16_f32 v82, v86, v87
	v_lshlrev_b32_e32 v86, 16, v140
	v_cvt_pk_bf16_f32 v83, v88, v89
	v_cvt_pk_bf16_f32 v84, v84, v85
	v_cvt_pk_bf16_f32 v85, v90, v91
	global_store_dwordx4 v[214:215], v[82:85], off offset:256
	v_add_co_u32_e32 v250, vcc, 0x1e0000, v206
	s_nop 1
	v_addc_co_u32_e32 v251, vcc, 0, v207, vcc
	v_add_co_u32_e32 v252, vcc, 0xa0000, v208
	s_nop 1
	v_addc_co_u32_e32 v253, vcc, 0, v209, vcc
	global_load_dwordx4 v[116:119], v[250:251], off offset:256
	global_load_dwordx4 v[120:123], v[252:253], off offset:256
	v_and_b32_e32 v87, 0xffff0000, v140
	v_lshlrev_b32_e32 v88, 16, v141
	v_lshlrev_b32_e32 v82, 16, v138
	v_and_b32_e32 v83, 0xffff0000, v138
	v_lshlrev_b32_e32 v84, 16, v139
	v_and_b32_e32 v85, 0xffff0000, v139
	v_and_b32_e32 v89, 0xffff0000, v141
	v_lshlrev_b32_e32 v90, 16, v142
	v_and_b32_e32 v91, 0xffff0000, v142
	v_lshlrev_b32_e32 v92, 16, v143
	v_and_b32_e32 v93, 0xffff0000, v143
	v_lshlrev_b32_e32 v94, 16, v144
	v_and_b32_e32 v95, 0xffff0000, v144
	v_lshlrev_b32_e32 v96, 16, v145
	v_and_b32_e32 v97, 0xffff0000, v145
	v_pk_fma_f32 v[80:81], v[80:81], v[84:85], v[92:93]
	v_pk_fma_f32 v[78:79], v[78:79], v[82:83], v[90:91]
	v_pk_fma_f32 v[82:83], v[76:77], v[88:89], v[96:97]
	v_pk_fma_f32 v[76:77], v[74:75], v[86:87], v[94:95]
; __device__ __forceinline__ u32x4 pack8(const f32x4 v0, const f32x4 v1) { u32x4 w; w.x = cvt_pk_bf16(v0[0], v0[1]); w.y = cvt_pk_bf16(v0[2], v0[3]); w.z = cvt_pk_bf16(v1[0], v1[1]); w.w = cvt_pk_bf16(v1[2], v1[3]); return w; }
;     __device__ __forceinline__ void operator()(const f32x4 (&acc)[2][2][4][2], const Unit& u, int wr, int wc, int fr_, int fq) const {
;     ...
;                 for (int bj = 0; bj < 2; ++bj) { const size_t r = row0 + ai * HALF + m * 16; const int c = col0 + bj * HALF;
;                     gw[m][bj] = *(const u32x4*)(G + r * 6144 + goff + c); if (!FIRST) ow[m][bj] = *(const u32x4*)(Mo + r * DM + c); }
; #pragma unroll
;             for (int m = 0; m < 4; ++m)
; #pragma unroll
;                 for (int bj = 0; bj < 2; ++bj) { const size_t r = row0 + ai * HALF + m * 16; const int c = col0 + bj * HALF;
;                     f32x4 g0, g1; unpack8(gw[m][bj], g0, g1);
;                     f32x4 v0 = g0 * acc[ai][bj][m][0], v1 = g1 * acc[ai][bj][m][1];
;                     if (!FIRST) { f32x4 o0, o1; unpack8(ow[m][bj], o0, o1); v0 += o0; v1 += o1; }
;                     *(u32x4*)((Mdst ? Mdst : Mo) + r * DM + c) = pack8(v0, v1); }
;             asm volatile("" ::: "memory"); }
	v_cvt_pk_bf16_f32 v74, v78, v79
	v_cvt_pk_bf16_f32 v75, v80, v81
	v_lshlrev_b32_e32 v78, 16, v136
	v_cvt_pk_bf16_f32 v76, v76, v77
	v_cvt_pk_bf16_f32 v77, v82, v83
	global_store_dwordx4 v[212:213], v[74:77], off
	v_add_co_u32_e32 v250, vcc, 0x210000, v206
	s_nop 1
	v_addc_co_u32_e32 v251, vcc, 0, v207, vcc
	v_add_co_u32_e32 v252, vcc, 0xb0000, v208
	s_nop 1
	v_addc_co_u32_e32 v253, vcc, 0, v209, vcc
	global_load_dwordx4 v[212:215], v[250:251], off
	global_load_dwordx4 v[216:219], v[252:253], off
	v_and_b32_e32 v79, 0xffff0000, v136
	v_lshlrev_b32_e32 v80, 16, v137
	v_lshlrev_b32_e32 v74, 16, v134
	v_and_b32_e32 v75, 0xffff0000, v134
	v_and_b32_e32 v81, 0xffff0000, v137
	v_lshlrev_b32_e32 v82, 16, v130
	v_and_b32_e32 v83, 0xffff0000, v130
	v_lshlrev_b32_e32 v86, 16, v132
	v_and_b32_e32 v87, 0xffff0000, v132
	v_lshlrev_b32_e32 v88, 16, v133
	v_and_b32_e32 v89, 0xffff0000, v133
	v_lshlrev_b32_e32 v76, 16, v135
	v_and_b32_e32 v77, 0xffff0000, v135
	v_lshlrev_b32_e32 v84, 16, v131
	v_and_b32_e32 v85, 0xffff0000, v131
	v_pk_fma_f32 v[70:71], v[70:71], v[74:75], v[82:83]
	v_pk_fma_f32 v[74:75], v[68:69], v[80:81], v[88:89]
	v_pk_fma_f32 v[68:69], v[66:67], v[78:79], v[86:87]
	v_pk_fma_f32 v[72:73], v[72:73], v[76:77], v[84:85]
	v_cvt_pk_bf16_f32 v66, v70, v71
	v_lshl_add_u64 v[106:107], v[208:209], 0, s[34:35]
	v_cvt_pk_bf16_f32 v67, v72, v73
	v_cvt_pk_bf16_f32 v68, v68, v69
	v_cvt_pk_bf16_f32 v69, v74, v75
	global_store_dwordx4 v[210:211], v[66:69], off offset:256
	v_add_co_u32_e32 v250, vcc, 0x210000, v206
	s_nop 1
	v_addc_co_u32_e32 v251, vcc, 0, v207, vcc
	v_add_co_u32_e32 v252, vcc, 0xb0000, v208
	s_nop 1
	v_addc_co_u32_e32 v253, vcc, 0, v209, vcc
	global_load_dwordx4 v[134:137], v[250:251], off offset:256
	global_load_dwordx4 v[130:133], v[252:253], off offset:256
	s_nop 1
	s_nop 0
	v_add_co_u32_e32 v142, vcc, s52, v208
	s_mov_b64 s[30:31], 0x80000
	s_nop 0
	v_addc_co_u32_e32 v143, vcc, 0, v209, vcc
	v_lshl_add_u64 v[140:141], v[208:209], 0, s[30:31]
	s_mov_b32 s1, 0x1b0000
	s_mov_b64 s[30:31], 0x1b0000
	s_nop 0
	v_add_co_u32_e32 v144, vcc, s0, v208
	s_nop 0
	v_addc_co_u32_e32 v145, vcc, 0, v209, vcc
	s_mov_b64 s[0:1], 0x1e0000
	s_mov_b32 s0, 0x1e0000
	s_mov_b64 s[0:1], 0xa0000
	s_nop 0
	v_lshl_add_u64 v[102:103], v[208:209], 0, s[0:1]
	s_mov_b32 s0, 0xa0000
	v_add_co_u32_e32 v104, vcc, s0, v208
	s_mov_b64 s[0:1], 0x210000
	s_nop 0
	v_addc_co_u32_e32 v105, vcc, 0, v209, vcc
	s_mov_b32 s0, 0x210000
	s_mov_b64 s[0:1], 0xb0000
	s_nop 0
	v_lshl_add_u64 v[98:99], v[208:209], 0, s[0:1]
	s_mov_b32 s0, 0xb0000
	v_add_co_u32_e32 v100, vcc, s0, v208
	s_mov_b64 s[0:1], -1
	s_nop 0
	v_addc_co_u32_e32 v101, vcc, 0, v209, vcc
	s_nop 0
	s_andn2_b64 vcc, exec, s[6:7]
	s_waitcnt vmcnt(22)
	v_lshlrev_b32_e32 v146, 16, v226
	v_and_b32_e32 v147, 0xffff0000, v226
	v_lshlrev_b32_e32 v108, 16, v227
	v_and_b32_e32 v109, 0xffff0000, v227
	v_lshlrev_b32_e32 v148, 16, v228
	v_and_b32_e32 v149, 0xffff0000, v228
	v_lshlrev_b32_e32 v110, 16, v229
	v_and_b32_e32 v111, 0xffff0000, v229
	s_waitcnt vmcnt(21)
	v_lshlrev_b32_e32 v150, 16, v244
	v_and_b32_e32 v151, 0xffff0000, v244
	v_lshlrev_b32_e32 v112, 16, v245
	v_and_b32_e32 v113, 0xffff0000, v245
	v_lshlrev_b32_e32 v152, 16, v246
	v_and_b32_e32 v153, 0xffff0000, v246
	v_lshlrev_b32_e32 v114, 16, v247
	v_and_b32_e32 v115, 0xffff0000, v247
	v_pk_fma_f32 v[64:65], v[64:65], v[108:109], v[112:113]
	v_pk_fma_f32 v[62:63], v[62:63], v[146:147], v[150:151]
	v_pk_fma_f32 v[108:109], v[60:61], v[110:111], v[114:115]
	v_pk_fma_f32 v[60:61], v[58:59], v[148:149], v[152:153]
	v_cvt_pk_bf16_f32 v58, v62, v63
	v_cvt_pk_bf16_f32 v59, v64, v65
	s_waitcnt vmcnt(19)
	v_lshlrev_b32_e32 v62, 16, v184
	v_cvt_pk_bf16_f32 v60, v60, v61
	v_cvt_pk_bf16_f32 v61, v108, v109
	global_store_dwordx4 v[142:143], v[58:61], off
	v_and_b32_e32 v63, 0xffff0000, v184
	v_lshlrev_b32_e32 v64, 16, v185
	v_lshlrev_b32_e32 v58, 16, v182
	v_and_b32_e32 v59, 0xffff0000, v182
	v_and_b32_e32 v65, 0xffff0000, v185
	s_waitcnt vmcnt(19)
	v_lshlrev_b32_e32 v108, 16, v178
	v_and_b32_e32 v109, 0xffff0000, v178
	v_lshlrev_b32_e32 v112, 16, v180
	v_and_b32_e32 v113, 0xffff0000, v180
	v_lshlrev_b32_e32 v114, 16, v181
	v_and_b32_e32 v115, 0xffff0000, v181
	v_lshlrev_b32_e32 v60, 16, v183
	v_and_b32_e32 v61, 0xffff0000, v183
	v_lshlrev_b32_e32 v110, 16, v179
	v_and_b32_e32 v111, 0xffff0000, v179
	v_pk_fma_f32 v[54:55], v[54:55], v[58:59], v[108:109]
	v_pk_fma_f32 v[58:59], v[52:53], v[64:65], v[114:115]
	v_pk_fma_f32 v[52:53], v[50:51], v[62:63], v[112:113]
	v_pk_fma_f32 v[56:57], v[56:57], v[60:61], v[110:111]
	v_cvt_pk_bf16_f32 v50, v54, v55
	s_waitcnt vmcnt(17)
	v_lshlrev_b32_e32 v54, 16, v172
	v_cvt_pk_bf16_f32 v51, v56, v57
	v_cvt_pk_bf16_f32 v52, v52, v53
	v_cvt_pk_bf16_f32 v53, v58, v59
	global_store_dwordx4 v[140:141], v[50:53], off offset:256
	v_and_b32_e32 v55, 0xffff0000, v172
	v_lshlrev_b32_e32 v56, 16, v173
	v_lshlrev_b32_e32 v50, 16, v170
	v_and_b32_e32 v51, 0xffff0000, v170
	v_lshlrev_b32_e32 v52, 16, v171
	v_and_b32_e32 v53, 0xffff0000, v171
	v_and_b32_e32 v57, 0xffff0000, v173
	s_waitcnt vmcnt(17)
	v_lshlrev_b32_e32 v58, 16, v174
	v_and_b32_e32 v59, 0xffff0000, v174
	v_lshlrev_b32_e32 v60, 16, v175
	v_and_b32_e32 v61, 0xffff0000, v175
	v_lshlrev_b32_e32 v62, 16, v176
	v_and_b32_e32 v63, 0xffff0000, v176
	v_lshlrev_b32_e32 v64, 16, v177
	v_and_b32_e32 v65, 0xffff0000, v177
	v_pk_fma_f32 v[48:49], v[48:49], v[52:53], v[60:61]
	v_pk_fma_f32 v[46:47], v[46:47], v[50:51], v[58:59]
	v_pk_fma_f32 v[50:51], v[44:45], v[56:57], v[64:65]
	v_pk_fma_f32 v[44:45], v[42:43], v[54:55], v[62:63]
	v_cvt_pk_bf16_f32 v42, v46, v47
	v_cvt_pk_bf16_f32 v43, v48, v49
	s_waitcnt vmcnt(15)
; __device__ __forceinline__ u32x4 pack8(const f32x4 v0, const f32x4 v1) { u32x4 w; w.x = cvt_pk_bf16(v0[0], v0[1]); w.y = cvt_pk_bf16(v0[2], v0[3]); w.z = cvt_pk_bf16(v1[0], v1[1]); w.w = cvt_pk_bf16(v1[2], v1[3]); return w; }
;     __device__ __forceinline__ void operator()(const f32x4 (&acc)[2][2][4][2], const Unit& u, int wr, int wc, int fr_, int fq) const {
;     ...
;             for (int m = 0; m < 4; ++m)
; #pragma unroll
;                 for (int bj = 0; bj < 2; ++bj) { const size_t r = row0 + ai * HALF + m * 16; const int c = col0 + bj * HALF;
;                     f32x4 g0, g1; unpack8(gw[m][bj], g0, g1);
;                     f32x4 v0 = g0 * acc[ai][bj][m][0], v1 = g1 * acc[ai][bj][m][1];
;                     if (!FIRST) { f32x4 o0, o1; unpack8(ow[m][bj], o0, o1); v0 += o0; v1 += o1; }
;                     *(u32x4*)((Mdst ? Mdst : Mo) + r * DM + c) = pack8(v0, v1); }
;             asm volatile("" ::: "memory"); }
	v_lshlrev_b32_e32 v46, 16, v168
	v_cvt_pk_bf16_f32 v44, v44, v45
	v_cvt_pk_bf16_f32 v45, v50, v51
	global_store_dwordx4 v[144:145], v[42:45], off
	v_and_b32_e32 v47, 0xffff0000, v168
	v_lshlrev_b32_e32 v48, 16, v169
	v_lshlrev_b32_e32 v42, 16, v166
	v_and_b32_e32 v43, 0xffff0000, v166
	v_and_b32_e32 v49, 0xffff0000, v169
	s_waitcnt vmcnt(15)
	v_lshlrev_b32_e32 v50, 16, v162
	v_and_b32_e32 v51, 0xffff0000, v162
	v_lshlrev_b32_e32 v54, 16, v164
	v_and_b32_e32 v55, 0xffff0000, v164
	v_lshlrev_b32_e32 v56, 16, v165
	v_and_b32_e32 v57, 0xffff0000, v165
	v_lshlrev_b32_e32 v44, 16, v167
	v_and_b32_e32 v45, 0xffff0000, v167
	v_lshlrev_b32_e32 v52, 16, v163
	v_and_b32_e32 v53, 0xffff0000, v163
	v_pk_fma_f32 v[38:39], v[38:39], v[42:43], v[50:51]
	v_pk_fma_f32 v[42:43], v[36:37], v[48:49], v[56:57]
	v_pk_fma_f32 v[36:37], v[34:35], v[46:47], v[54:55]
	v_pk_fma_f32 v[40:41], v[40:41], v[44:45], v[52:53]
	v_cvt_pk_bf16_f32 v34, v38, v39
	s_waitcnt vmcnt(13)
	v_lshlrev_b32_e32 v38, 16, v156
	v_cvt_pk_bf16_f32 v35, v40, v41
	v_cvt_pk_bf16_f32 v36, v36, v37
	v_cvt_pk_bf16_f32 v37, v42, v43
	global_store_dwordx4 v[106:107], v[34:37], off offset:256
	v_and_b32_e32 v39, 0xffff0000, v156
	v_lshlrev_b32_e32 v40, 16, v157
	v_lshlrev_b32_e32 v34, 16, v154
	v_and_b32_e32 v35, 0xffff0000, v154
	v_lshlrev_b32_e32 v36, 16, v155
	v_and_b32_e32 v37, 0xffff0000, v155
	v_and_b32_e32 v41, 0xffff0000, v157
	s_waitcnt vmcnt(13)
	v_lshlrev_b32_e32 v42, 16, v158
	v_and_b32_e32 v43, 0xffff0000, v158
	v_lshlrev_b32_e32 v44, 16, v159
	v_and_b32_e32 v45, 0xffff0000, v159
	v_lshlrev_b32_e32 v46, 16, v160
	v_and_b32_e32 v47, 0xffff0000, v160
	v_lshlrev_b32_e32 v48, 16, v161
	v_and_b32_e32 v49, 0xffff0000, v161
	v_pk_fma_f32 v[32:33], v[32:33], v[36:37], v[44:45]
	v_pk_fma_f32 v[30:31], v[30:31], v[34:35], v[42:43]
	v_pk_fma_f32 v[34:35], v[28:29], v[40:41], v[48:49]
	v_pk_fma_f32 v[28:29], v[26:27], v[38:39], v[46:47]
	v_cvt_pk_bf16_f32 v26, v30, v31
	v_cvt_pk_bf16_f32 v27, v32, v33
	s_waitcnt vmcnt(11)
	v_lshlrev_b32_e32 v30, 16, v118
	v_cvt_pk_bf16_f32 v28, v28, v29
	v_cvt_pk_bf16_f32 v29, v34, v35
	global_store_dwordx4 v[104:105], v[26:29], off
	v_and_b32_e32 v31, 0xffff0000, v118
	v_lshlrev_b32_e32 v32, 16, v119
	v_lshlrev_b32_e32 v26, 16, v116
	v_and_b32_e32 v27, 0xffff0000, v116
	v_and_b32_e32 v33, 0xffff0000, v119
	s_waitcnt vmcnt(11)
	v_lshlrev_b32_e32 v34, 16, v120
	v_and_b32_e32 v35, 0xffff0000, v120
	v_lshlrev_b32_e32 v38, 16, v122
	v_and_b32_e32 v39, 0xffff0000, v122
	v_lshlrev_b32_e32 v40, 16, v123
	v_and_b32_e32 v41, 0xffff0000, v123
	v_lshlrev_b32_e32 v28, 16, v117
	v_and_b32_e32 v29, 0xffff0000, v117
	v_lshlrev_b32_e32 v36, 16, v121
	v_and_b32_e32 v37, 0xffff0000, v121
	v_pk_fma_f32 v[22:23], v[22:23], v[26:27], v[34:35]
	v_pk_fma_f32 v[26:27], v[20:21], v[32:33], v[40:41]
	v_pk_fma_f32 v[20:21], v[18:19], v[30:31], v[38:39]
	v_pk_fma_f32 v[24:25], v[24:25], v[28:29], v[36:37]
	v_cvt_pk_bf16_f32 v18, v22, v23
	s_waitcnt vmcnt(9)
	v_lshlrev_b32_e32 v22, 16, v214
	v_cvt_pk_bf16_f32 v19, v24, v25
	v_cvt_pk_bf16_f32 v20, v20, v21
	v_cvt_pk_bf16_f32 v21, v26, v27
	global_store_dwordx4 v[102:103], v[18:21], off offset:256
	v_and_b32_e32 v23, 0xffff0000, v214
	v_lshlrev_b32_e32 v24, 16, v215
	v_lshlrev_b32_e32 v18, 16, v212
	v_and_b32_e32 v19, 0xffff0000, v212
	v_lshlrev_b32_e32 v20, 16, v213
	v_and_b32_e32 v21, 0xffff0000, v213
	v_and_b32_e32 v25, 0xffff0000, v215
	s_waitcnt vmcnt(9)
	v_lshlrev_b32_e32 v26, 16, v216
	v_and_b32_e32 v27, 0xffff0000, v216
	v_lshlrev_b32_e32 v28, 16, v217
	v_and_b32_e32 v29, 0xffff0000, v217
	v_lshlrev_b32_e32 v30, 16, v218
	v_and_b32_e32 v31, 0xffff0000, v218
	v_lshlrev_b32_e32 v32, 16, v219
	v_and_b32_e32 v33, 0xffff0000, v219
	v_pk_fma_f32 v[16:17], v[16:17], v[20:21], v[28:29]
	v_pk_fma_f32 v[14:15], v[14:15], v[18:19], v[26:27]
	v_pk_fma_f32 v[18:19], v[12:13], v[24:25], v[32:33]
	v_pk_fma_f32 v[12:13], v[10:11], v[22:23], v[30:31]
	v_cvt_pk_bf16_f32 v10, v14, v15
	v_cvt_pk_bf16_f32 v11, v16, v17
	s_waitcnt vmcnt(7)
	v_lshlrev_b32_e32 v14, 16, v136
	v_cvt_pk_bf16_f32 v12, v12, v13
	v_cvt_pk_bf16_f32 v13, v18, v19
	global_store_dwordx4 v[100:101], v[10:13], off
	v_and_b32_e32 v15, 0xffff0000, v136
	v_lshlrev_b32_e32 v16, 16, v137
	v_lshlrev_b32_e32 v10, 16, v134
	v_and_b32_e32 v11, 0xffff0000, v134
	v_and_b32_e32 v17, 0xffff0000, v137
	s_waitcnt vmcnt(7)
	v_lshlrev_b32_e32 v18, 16, v130
	v_and_b32_e32 v19, 0xffff0000, v130
	v_lshlrev_b32_e32 v22, 16, v132
	v_and_b32_e32 v23, 0xffff0000, v132
	v_lshlrev_b32_e32 v24, 16, v133
	v_and_b32_e32 v25, 0xffff0000, v133
	v_lshlrev_b32_e32 v12, 16, v135
	v_and_b32_e32 v13, 0xffff0000, v135
	v_lshlrev_b32_e32 v20, 16, v131
	v_and_b32_e32 v21, 0xffff0000, v131
	v_pk_fma_f32 v[6:7], v[6:7], v[10:11], v[18:19]
	v_pk_fma_f32 v[10:11], v[4:5], v[16:17], v[24:25]
	v_pk_fma_f32 v[4:5], v[2:3], v[14:15], v[22:23]
	v_pk_fma_f32 v[8:9], v[8:9], v[12:13], v[20:21]
	v_cvt_pk_bf16_f32 v2, v6, v7
	s_nop 0
	v_cvt_pk_bf16_f32 v3, v8, v9
	v_cvt_pk_bf16_f32 v4, v4, v5
	v_cvt_pk_bf16_f32 v5, v10, v11
	global_store_dwordx4 v[98:99], v[2:5], off offset:256
	s_cbranch_vccnz .LBB0_1133
	s_andn2_b64 vcc, exec, s[12:13]
	s_cbranch_vccnz .LBB0_1132
	s_barrier
	s_branch .LBB0_1132

; __device__ __forceinline__ u32x4 pack8(const f32x4 v0, const f32x4 v1) { u32x4 w; w.x = cvt_pk_bf16(v0[0], v0[1]); w.y = cvt_pk_bf16(v0[2], v0[3]); w.z = cvt_pk_bf16(v1[0], v1[1]); w.w = cvt_pk_bf16(v1[2], v1[3]); return w; }
;     __device__ __forceinline__ void operator()(const f32x4 (&acc)[2][2][4][2], const Unit& u, int wr, int wc, int fr_, int fq) const {
;     ...
;         const size_t row0 = (size_t)u.pm * BM + wr * 64 + fr; const int col0 = u.pn * BM + wc * 32 + 8 * fq;
; #pragma unroll
;         for (int ai = 0; ai < 2; ++ai) {
;             u32x4 gw[4][2], ow[4][2];
; #pragma unroll
;             for (int m = 0; m < 4; ++m)
; #pragma unroll
;                 for (int bj = 0; bj < 2; ++bj) { const size_t r = row0 + ai * HALF + m * 16; const int c = col0 + bj * HALF;
;                     gw[m][bj] = *(const u32x4*)(G + r * 6144 + goff + c); if (!FIRST) ow[m][bj] = *(const u32x4*)(Mo + r * DM + c); }
; #pragma unroll
;             for (int m = 0; m < 4; ++m)
; #pragma unroll
;                 for (int bj = 0; bj < 2; ++bj) { const size_t r = row0 + ai * HALF + m * 16; const int c = col0 + bj * HALF;
;                     f32x4 g0, g1; unpack8(gw[m][bj], g0, g1);
;                     f32x4 v0 = g0 * acc[ai][bj][m][0], v1 = g1 * acc[ai][bj][m][1];
;                     if (!FIRST) { f32x4 o0, o1; unpack8(ow[m][bj], o0, o1); v0 += o0; v1 += o1; }
;                     *(u32x4*)((Mdst ? Mdst : Mo) + r * DM + c) = pack8(v0, v1); }
;             asm volatile("" ::: "memory"); }
.LBB0_1166:
	s_ashr_i32 s29, s28, 31
	s_lshl_b64 s[0:1], s[28:29], 8
	v_mov_b32_e32 v130, v222
	s_add_u32 s0, s0, s68
	s_addc_u32 s1, s1, s81
	v_ashrrev_i32_e32 v131, 31, v130
	v_lshl_add_u64 v[130:131], s[0:1], 0, v[130:131]
	v_lshl_or_b32 v132, s26, 8, v224
	v_mov_b64_e32 v[134:135], s[14:15]
	s_movk_i32 s19, 0x3000
	v_ashrrev_i32_e32 v133, 31, v132
	v_mad_u64_u32 v[134:135], s[0:1], v130, s19, v[134:135]
	v_mad_i32_i24 v135, v131, s19, v135
	v_lshlrev_b64 v[132:133], 1, v[132:133]
	v_lshlrev_b64 v[130:131], 12, v[130:131]
	v_lshl_add_u64 v[206:207], v[134:135], 0, v[132:133]
	v_lshl_add_u64 v[130:131], s[2:3], 0, v[130:131]
	global_load_dwordx4 v[226:229], v[206:207], off
	v_lshl_add_u64 v[208:209], v[130:131], 0, v[132:133]
	global_load_dwordx4 v[244:247], v[208:209], off
	global_load_dwordx4 v[182:185], v[206:207], off offset:256
	global_load_dwordx4 v[178:181], v[208:209], off offset:256
	v_add_co_u32_e32 v132, vcc, s91, v206
	s_mov_b64 s[28:29], 0x30000
	s_nop 0
	v_addc_co_u32_e32 v133, vcc, 0, v207, vcc
	global_load_dwordx4 v[170:173], v[132:133], off
	v_add_co_u32_e32 v220, vcc, s80, v208
	v_lshl_add_u64 v[130:131], v[206:207], 0, s[28:29]
	s_nop 0
	v_addc_co_u32_e32 v221, vcc, 0, v209, vcc
	v_lshl_add_u64 v[218:219], v[208:209], 0, s[48:49]
	global_load_dwordx4 v[174:177], v[220:221], off
	global_load_dwordx4 v[166:169], v[130:131], off offset:256
	global_load_dwordx4 v[162:165], v[218:219], off offset:256
	v_add_co_u32_e32 v132, vcc, s94, v206
	s_mov_b64 s[0:1], 0x60000
	s_nop 0
	v_addc_co_u32_e32 v133, vcc, 0, v207, vcc
	global_load_dwordx4 v[154:157], v[132:133], off
	v_add_co_u32_e32 v216, vcc, s95, v208
	v_lshl_add_u64 v[130:131], v[206:207], 0, s[0:1]
	s_mov_b64 s[0:1], 0x20000
	v_addc_co_u32_e32 v217, vcc, 0, v209, vcc
	v_lshl_add_u64 v[214:215], v[208:209], 0, s[0:1]
	global_load_dwordx4 v[158:161], v[216:217], off
	global_load_dwordx4 v[150:153], v[130:131], off offset:256
	global_load_dwordx4 v[146:149], v[214:215], off offset:256
	s_mov_b32 s0, 0x90000
	v_add_co_u32_e32 v132, vcc, s0, v206
	s_mov_b64 s[30:31], 0x90000
	s_nop 0
	v_addc_co_u32_e32 v133, vcc, 0, v207, vcc
	global_load_dwordx4 v[138:141], v[132:133], off
	v_add_co_u32_e32 v212, vcc, s91, v208
	v_lshl_add_u64 v[130:131], v[206:207], 0, s[30:31]
	s_nop 0
	v_addc_co_u32_e32 v213, vcc, 0, v209, vcc
	v_lshl_add_u64 v[210:211], v[208:209], 0, s[28:29]
	global_load_dwordx4 v[142:145], v[212:213], off
	global_load_dwordx4 v[134:137], v[130:131], off offset:256
	s_nop 0
	global_load_dwordx4 v[130:133], v[210:211], off offset:256
	s_mov_b32 s1, 0x180000
	s_mov_b32 s52, 0x80000
	s_mov_b64 s[28:29], 0x180000
	s_mov_b32 s86, 0x9000
	s_mov_b32 s88, 0xf800000
	s_movk_i32 s89, 0xffe0
	s_waitcnt vmcnt(0)
	v_lshlrev_b32_e32 v248, 16, v246
	v_lshlrev_b32_e32 v188, 16, v226
	v_and_b32_e32 v189, 0xffff0000, v226
	v_lshlrev_b32_e32 v190, 16, v227
	v_and_b32_e32 v191, 0xffff0000, v227
	v_lshlrev_b32_e32 v192, 16, v228
	v_and_b32_e32 v193, 0xffff0000, v228
	v_lshlrev_b32_e32 v226, 16, v229
	v_and_b32_e32 v227, 0xffff0000, v229
	v_lshlrev_b32_e32 v228, 16, v244
	v_and_b32_e32 v229, 0xffff0000, v244
	v_and_b32_e32 v249, 0xffff0000, v246
	v_lshlrev_b32_e32 v246, 16, v247
	v_and_b32_e32 v247, 0xffff0000, v247
	v_lshlrev_b32_e32 v244, 16, v245
	v_and_b32_e32 v245, 0xffff0000, v245
	v_pk_fma_f32 v[126:127], v[126:127], v[188:189], v[228:229]
	v_pk_fma_f32 v[188:189], v[124:125], v[226:227], v[246:247]
	v_pk_fma_f32 v[124:125], v[122:123], v[192:193], v[248:249]
	v_pk_fma_f32 v[128:129], v[128:129], v[190:191], v[244:245]
	v_cvt_pk_bf16_f32 v122, v126, v127
	v_lshlrev_b32_e32 v126, 16, v184
	v_cvt_pk_bf16_f32 v123, v128, v129
	v_cvt_pk_bf16_f32 v124, v124, v125
	v_cvt_pk_bf16_f32 v125, v188, v189
	global_store_dwordx4 v[208:209], v[122:125], off
	v_add_co_u32_e32 v250, vcc, 0x180000, v206
	s_nop 1
	v_addc_co_u32_e32 v251, vcc, 0, v207, vcc
	v_add_co_u32_e32 v252, vcc, 0x80000, v208
	s_nop 1
	v_addc_co_u32_e32 v253, vcc, 0, v209, vcc
	global_load_dwordx4 v[226:229], v[250:251], off
	global_load_dwordx4 v[244:247], v[252:253], off
	v_and_b32_e32 v127, 0xffff0000, v184
	v_lshlrev_b32_e32 v128, 16, v185
	v_lshlrev_b32_e32 v122, 16, v182
	v_and_b32_e32 v123, 0xffff0000, v182
	v_lshlrev_b32_e32 v124, 16, v183
	v_and_b32_e32 v125, 0xffff0000, v183
	v_and_b32_e32 v129, 0xffff0000, v185
	v_lshlrev_b32_e32 v182, 16, v178
	v_and_b32_e32 v183, 0xffff0000, v178
	v_lshlrev_b32_e32 v184, 16, v180
	v_and_b32_e32 v185, 0xffff0000, v180
	v_lshlrev_b32_e32 v180, 16, v181
	v_and_b32_e32 v181, 0xffff0000, v181
	v_lshlrev_b32_e32 v178, 16, v179
	v_and_b32_e32 v179, 0xffff0000, v179
	v_pk_fma_f32 v[118:119], v[118:119], v[122:123], v[182:183]
	v_pk_fma_f32 v[122:123], v[116:117], v[128:129], v[180:181]
	v_pk_fma_f32 v[116:117], v[114:115], v[126:127], v[184:185]
	v_pk_fma_f32 v[120:121], v[120:121], v[124:125], v[178:179]
	v_cvt_pk_bf16_f32 v114, v118, v119
	v_lshlrev_b32_e32 v118, 16, v172
	v_cvt_pk_bf16_f32 v115, v120, v121
	v_cvt_pk_bf16_f32 v116, v116, v117
	v_cvt_pk_bf16_f32 v117, v122, v123
	global_store_dwordx4 v[208:209], v[114:117], off offset:256
	v_add_co_u32_e32 v250, vcc, 0x180000, v206
	s_nop 1
	v_addc_co_u32_e32 v251, vcc, 0, v207, vcc
	v_add_co_u32_e32 v252, vcc, 0x80000, v208
	s_nop 1
	v_addc_co_u32_e32 v253, vcc, 0, v209, vcc
	global_load_dwordx4 v[182:185], v[250:251], off offset:256
	global_load_dwordx4 v[178:181], v[252:253], off offset:256
	v_and_b32_e32 v119, 0xffff0000, v172
	v_lshlrev_b32_e32 v120, 16, v173
	v_lshlrev_b32_e32 v114, 16, v170
	v_and_b32_e32 v115, 0xffff0000, v170
	v_lshlrev_b32_e32 v116, 16, v171
	v_and_b32_e32 v117, 0xffff0000, v171
	v_and_b32_e32 v121, 0xffff0000, v173
; __device__ __forceinline__ u32x4 pack8(const f32x4 v0, const f32x4 v1) { u32x4 w; w.x = cvt_pk_bf16(v0[0], v0[1]); w.y = cvt_pk_bf16(v0[2], v0[3]); w.z = cvt_pk_bf16(v1[0], v1[1]); w.w = cvt_pk_bf16(v1[2], v1[3]); return w; }
;     __device__ __forceinline__ void operator()(const f32x4 (&acc)[2][2][4][2], const Unit& u, int wr, int wc, int fr_, int fq) const {
;     ...
;             for (int m = 0; m < 4; ++m)
; #pragma unroll
;                 for (int bj = 0; bj < 2; ++bj) { const size_t r = row0 + ai * HALF + m * 16; const int c = col0 + bj * HALF;
;                     f32x4 g0, g1; unpack8(gw[m][bj], g0, g1);
;                     f32x4 v0 = g0 * acc[ai][bj][m][0], v1 = g1 * acc[ai][bj][m][1];
;                     if (!FIRST) { f32x4 o0, o1; unpack8(ow[m][bj], o0, o1); v0 += o0; v1 += o1; }
;                     *(u32x4*)((Mdst ? Mdst : Mo) + r * DM + c) = pack8(v0, v1); }
;             asm volatile("" ::: "memory"); }
	v_lshlrev_b32_e32 v122, 16, v174
	v_and_b32_e32 v123, 0xffff0000, v174
	v_lshlrev_b32_e32 v124, 16, v175
	v_and_b32_e32 v125, 0xffff0000, v175
	v_lshlrev_b32_e32 v126, 16, v176
	v_and_b32_e32 v127, 0xffff0000, v176
	v_lshlrev_b32_e32 v128, 16, v177
	v_and_b32_e32 v129, 0xffff0000, v177
	v_pk_fma_f32 v[112:113], v[112:113], v[116:117], v[124:125]
	v_pk_fma_f32 v[110:111], v[110:111], v[114:115], v[122:123]
	v_pk_fma_f32 v[114:115], v[108:109], v[120:121], v[128:129]
	v_pk_fma_f32 v[108:109], v[106:107], v[118:119], v[126:127]
	v_cvt_pk_bf16_f32 v106, v110, v111
	v_cvt_pk_bf16_f32 v107, v112, v113
	v_lshlrev_b32_e32 v110, 16, v168
	v_cvt_pk_bf16_f32 v108, v108, v109
	v_cvt_pk_bf16_f32 v109, v114, v115
	global_store_dwordx4 v[220:221], v[106:109], off
	v_add_co_u32_e32 v250, vcc, 0x1b0000, v206
	s_nop 1
	v_addc_co_u32_e32 v251, vcc, 0, v207, vcc
	v_add_co_u32_e32 v252, vcc, 0x90000, v208
	s_nop 1
	v_addc_co_u32_e32 v253, vcc, 0, v209, vcc
	global_load_dwordx4 v[170:173], v[250:251], off
	global_load_dwordx4 v[174:177], v[252:253], off
	v_and_b32_e32 v111, 0xffff0000, v168
	v_lshlrev_b32_e32 v112, 16, v169
	v_lshlrev_b32_e32 v106, 16, v166
	v_and_b32_e32 v107, 0xffff0000, v166
	v_and_b32_e32 v113, 0xffff0000, v169
	v_lshlrev_b32_e32 v114, 16, v162
	v_and_b32_e32 v115, 0xffff0000, v162
	v_lshlrev_b32_e32 v118, 16, v164
	v_and_b32_e32 v119, 0xffff0000, v164
	v_lshlrev_b32_e32 v120, 16, v165
	v_and_b32_e32 v121, 0xffff0000, v165
	v_lshlrev_b32_e32 v108, 16, v167
	v_and_b32_e32 v109, 0xffff0000, v167
	v_lshlrev_b32_e32 v116, 16, v163
	v_and_b32_e32 v117, 0xffff0000, v163
	v_pk_fma_f32 v[102:103], v[102:103], v[106:107], v[114:115]
	v_pk_fma_f32 v[106:107], v[100:101], v[112:113], v[120:121]
	v_pk_fma_f32 v[100:101], v[98:99], v[110:111], v[118:119]
	v_pk_fma_f32 v[104:105], v[104:105], v[108:109], v[116:117]
	v_cvt_pk_bf16_f32 v98, v102, v103
	v_lshlrev_b32_e32 v102, 16, v156
	v_cvt_pk_bf16_f32 v99, v104, v105
	v_cvt_pk_bf16_f32 v100, v100, v101
	v_cvt_pk_bf16_f32 v101, v106, v107
	global_store_dwordx4 v[218:219], v[98:101], off offset:256
	v_add_co_u32_e32 v250, vcc, 0x1b0000, v206
	s_nop 1
	v_addc_co_u32_e32 v251, vcc, 0, v207, vcc
	v_add_co_u32_e32 v252, vcc, 0x90000, v208
	s_nop 1
	v_addc_co_u32_e32 v253, vcc, 0, v209, vcc
	global_load_dwordx4 v[166:169], v[250:251], off offset:256
	global_load_dwordx4 v[162:165], v[252:253], off offset:256
	v_and_b32_e32 v103, 0xffff0000, v156
	v_lshlrev_b32_e32 v104, 16, v157
	v_lshlrev_b32_e32 v98, 16, v154
	v_and_b32_e32 v99, 0xffff0000, v154
	v_lshlrev_b32_e32 v100, 16, v155
	v_and_b32_e32 v101, 0xffff0000, v155
	v_and_b32_e32 v105, 0xffff0000, v157
	v_lshlrev_b32_e32 v106, 16, v158
	v_and_b32_e32 v107, 0xffff0000, v158
	v_lshlrev_b32_e32 v108, 16, v159
	v_and_b32_e32 v109, 0xffff0000, v159
	v_lshlrev_b32_e32 v110, 16, v160
	v_and_b32_e32 v111, 0xffff0000, v160
	v_lshlrev_b32_e32 v112, 16, v161
	v_and_b32_e32 v113, 0xffff0000, v161
	v_pk_fma_f32 v[96:97], v[96:97], v[100:101], v[108:109]
	v_pk_fma_f32 v[94:95], v[94:95], v[98:99], v[106:107]
	v_pk_fma_f32 v[98:99], v[92:93], v[104:105], v[112:113]
	v_pk_fma_f32 v[92:93], v[90:91], v[102:103], v[110:111]
	v_cvt_pk_bf16_f32 v90, v94, v95
	v_cvt_pk_bf16_f32 v91, v96, v97
	v_lshlrev_b32_e32 v94, 16, v152
	v_cvt_pk_bf16_f32 v92, v92, v93
	v_cvt_pk_bf16_f32 v93, v98, v99
	global_store_dwordx4 v[216:217], v[90:93], off
	v_add_co_u32_e32 v250, vcc, 0x1e0000, v206
	s_nop 1
	v_addc_co_u32_e32 v251, vcc, 0, v207, vcc
	v_add_co_u32_e32 v252, vcc, 0xa0000, v208
	s_nop 1
	v_addc_co_u32_e32 v253, vcc, 0, v209, vcc
	global_load_dwordx4 v[154:157], v[250:251], off
	global_load_dwordx4 v[158:161], v[252:253], off
	v_and_b32_e32 v95, 0xffff0000, v152
	v_lshlrev_b32_e32 v96, 16, v153
	v_lshlrev_b32_e32 v90, 16, v150
	v_and_b32_e32 v91, 0xffff0000, v150
	v_and_b32_e32 v97, 0xffff0000, v153
	v_lshlrev_b32_e32 v98, 16, v146
	v_and_b32_e32 v99, 0xffff0000, v146
	v_lshlrev_b32_e32 v102, 16, v148
	v_and_b32_e32 v103, 0xffff0000, v148
	v_lshlrev_b32_e32 v104, 16, v149
	v_and_b32_e32 v105, 0xffff0000, v149
	v_lshlrev_b32_e32 v92, 16, v151
	v_and_b32_e32 v93, 0xffff0000, v151
	v_lshlrev_b32_e32 v100, 16, v147
	v_and_b32_e32 v101, 0xffff0000, v147
	v_pk_fma_f32 v[86:87], v[86:87], v[90:91], v[98:99]
	v_pk_fma_f32 v[90:91], v[84:85], v[96:97], v[104:105]
	v_pk_fma_f32 v[84:85], v[82:83], v[94:95], v[102:103]
	v_pk_fma_f32 v[88:89], v[88:89], v[92:93], v[100:101]
	v_cvt_pk_bf16_f32 v82, v86, v87
	v_lshlrev_b32_e32 v86, 16, v140
	v_cvt_pk_bf16_f32 v83, v88, v89
	v_cvt_pk_bf16_f32 v84, v84, v85
	v_cvt_pk_bf16_f32 v85, v90, v91
	global_store_dwordx4 v[214:215], v[82:85], off offset:256
	v_add_co_u32_e32 v250, vcc, 0x1e0000, v206
	s_nop 1
	v_addc_co_u32_e32 v251, vcc, 0, v207, vcc
	v_add_co_u32_e32 v252, vcc, 0xa0000, v208
	s_nop 1
	v_addc_co_u32_e32 v253, vcc, 0, v209, vcc
	global_load_dwordx4 v[116:119], v[250:251], off offset:256
	global_load_dwordx4 v[120:123], v[252:253], off offset:256
	v_and_b32_e32 v87, 0xffff0000, v140
	v_lshlrev_b32_e32 v88, 16, v141
	v_lshlrev_b32_e32 v82, 16, v138
	v_and_b32_e32 v83, 0xffff0000, v138
	v_lshlrev_b32_e32 v84, 16, v139
	v_and_b32_e32 v85, 0xffff0000, v139
	v_and_b32_e32 v89, 0xffff0000, v141
	v_lshlrev_b32_e32 v90, 16, v142
	v_and_b32_e32 v91, 0xffff0000, v142
	v_lshlrev_b32_e32 v92, 16, v143
	v_and_b32_e32 v93, 0xffff0000, v143
	v_lshlrev_b32_e32 v94, 16, v144
	v_and_b32_e32 v95, 0xffff0000, v144
	v_lshlrev_b32_e32 v96, 16, v145
	v_and_b32_e32 v97, 0xffff0000, v145
	v_pk_fma_f32 v[80:81], v[80:81], v[84:85], v[92:93]
	v_pk_fma_f32 v[78:79], v[78:79], v[82:83], v[90:91]
	v_pk_fma_f32 v[82:83], v[76:77], v[88:89], v[96:97]
; __device__ __forceinline__ u32x4 pack8(const f32x4 v0, const f32x4 v1) { u32x4 w; w.x = cvt_pk_bf16(v0[0], v0[1]); w.y = cvt_pk_bf16(v0[2], v0[3]); w.z = cvt_pk_bf16(v1[0], v1[1]); w.w = cvt_pk_bf16(v1[2], v1[3]); return w; }
;     __device__ __forceinline__ void operator()(const f32x4 (&acc)[2][2][4][2], const Unit& u, int wr, int wc, int fr_, int fq) const {
;     ...
;                 for (int bj = 0; bj < 2; ++bj) { const size_t r = row0 + ai * HALF + m * 16; const int c = col0 + bj * HALF;
;                     gw[m][bj] = *(const u32x4*)(G + r * 6144 + goff + c); if (!FIRST) ow[m][bj] = *(const u32x4*)(Mo + r * DM + c); }
; #pragma unroll
;             for (int m = 0; m < 4; ++m)
; #pragma unroll
;                 for (int bj = 0; bj < 2; ++bj) { const size_t r = row0 + ai * HALF + m * 16; const int c = col0 + bj * HALF;
;                     f32x4 g0, g1; unpack8(gw[m][bj], g0, g1);
;                     f32x4 v0 = g0 * acc[ai][bj][m][0], v1 = g1 * acc[ai][bj][m][1];
;                     if (!FIRST) { f32x4 o0, o1; unpack8(ow[m][bj], o0, o1); v0 += o0; v1 += o1; }
;                     *(u32x4*)((Mdst ? Mdst : Mo) + r * DM + c) = pack8(v0, v1); }
;             asm volatile("" ::: "memory"); }
	v_pk_fma_f32 v[76:77], v[74:75], v[86:87], v[94:95]
	v_cvt_pk_bf16_f32 v74, v78, v79
	v_cvt_pk_bf16_f32 v75, v80, v81
	v_lshlrev_b32_e32 v78, 16, v136
	v_cvt_pk_bf16_f32 v76, v76, v77
	v_cvt_pk_bf16_f32 v77, v82, v83
	global_store_dwordx4 v[212:213], v[74:77], off
	v_add_co_u32_e32 v250, vcc, 0x210000, v206
	s_nop 1
	v_addc_co_u32_e32 v251, vcc, 0, v207, vcc
	v_add_co_u32_e32 v252, vcc, 0xb0000, v208
	s_nop 1
	v_addc_co_u32_e32 v253, vcc, 0, v209, vcc
	global_load_dwordx4 v[212:215], v[250:251], off
	global_load_dwordx4 v[216:219], v[252:253], off
	v_and_b32_e32 v79, 0xffff0000, v136
	v_lshlrev_b32_e32 v80, 16, v137
	v_lshlrev_b32_e32 v74, 16, v134
	v_and_b32_e32 v75, 0xffff0000, v134
	v_and_b32_e32 v81, 0xffff0000, v137
	v_lshlrev_b32_e32 v82, 16, v130
	v_and_b32_e32 v83, 0xffff0000, v130
	v_lshlrev_b32_e32 v86, 16, v132
	v_and_b32_e32 v87, 0xffff0000, v132
	v_lshlrev_b32_e32 v88, 16, v133
	v_and_b32_e32 v89, 0xffff0000, v133
	v_lshlrev_b32_e32 v76, 16, v135
	v_and_b32_e32 v77, 0xffff0000, v135
	v_lshlrev_b32_e32 v84, 16, v131
	v_and_b32_e32 v85, 0xffff0000, v131
	v_pk_fma_f32 v[70:71], v[70:71], v[74:75], v[82:83]
	v_pk_fma_f32 v[74:75], v[68:69], v[80:81], v[88:89]
	v_pk_fma_f32 v[68:69], v[66:67], v[78:79], v[86:87]
	v_pk_fma_f32 v[72:73], v[72:73], v[76:77], v[84:85]
	v_cvt_pk_bf16_f32 v66, v70, v71
	v_lshl_add_u64 v[106:107], v[208:209], 0, s[30:31]
	v_cvt_pk_bf16_f32 v67, v72, v73
	v_cvt_pk_bf16_f32 v68, v68, v69
	v_cvt_pk_bf16_f32 v69, v74, v75
	global_store_dwordx4 v[210:211], v[66:69], off offset:256
	v_add_co_u32_e32 v250, vcc, 0x210000, v206
	s_nop 1
	v_addc_co_u32_e32 v251, vcc, 0, v207, vcc
	v_add_co_u32_e32 v252, vcc, 0xb0000, v208
	s_nop 1
	v_addc_co_u32_e32 v253, vcc, 0, v209, vcc
	global_load_dwordx4 v[134:137], v[250:251], off offset:256
	global_load_dwordx4 v[130:133], v[252:253], off offset:256
	s_nop 1
	s_nop 0
	v_add_co_u32_e32 v142, vcc, s52, v208
	s_mov_b64 s[28:29], 0x80000
	s_nop 0
	v_addc_co_u32_e32 v143, vcc, 0, v209, vcc
	v_lshl_add_u64 v[140:141], v[208:209], 0, s[28:29]
	s_mov_b32 s1, 0x1b0000
	s_mov_b64 s[28:29], 0x1b0000
	s_nop 0
	v_add_co_u32_e32 v144, vcc, s0, v208
	s_nop 0
	v_addc_co_u32_e32 v145, vcc, 0, v209, vcc
	s_mov_b64 s[0:1], 0x1e0000
	s_mov_b32 s0, 0x1e0000
	s_mov_b64 s[0:1], 0xa0000
	s_nop 0
	v_lshl_add_u64 v[102:103], v[208:209], 0, s[0:1]
	s_mov_b32 s0, 0xa0000
	v_add_co_u32_e32 v104, vcc, s0, v208
	s_mov_b64 s[0:1], 0x210000
	s_nop 0
	v_addc_co_u32_e32 v105, vcc, 0, v209, vcc
	s_mov_b32 s0, 0x210000
	s_mov_b64 s[0:1], 0xb0000
	s_nop 0
	v_lshl_add_u64 v[98:99], v[208:209], 0, s[0:1]
	s_mov_b32 s0, 0xb0000
	v_add_co_u32_e32 v100, vcc, s0, v208
	s_mov_b64 s[0:1], -1
	s_nop 0
	v_addc_co_u32_e32 v101, vcc, 0, v209, vcc
	s_nop 0
	s_andn2_b64 vcc, exec, s[6:7]
	s_waitcnt vmcnt(22)
	v_lshlrev_b32_e32 v146, 16, v226
	v_and_b32_e32 v147, 0xffff0000, v226
	v_lshlrev_b32_e32 v108, 16, v227
	v_and_b32_e32 v109, 0xffff0000, v227
	v_lshlrev_b32_e32 v148, 16, v228
	v_and_b32_e32 v149, 0xffff0000, v228
	v_lshlrev_b32_e32 v110, 16, v229
	v_and_b32_e32 v111, 0xffff0000, v229
	s_waitcnt vmcnt(21)
	v_lshlrev_b32_e32 v150, 16, v244
	v_and_b32_e32 v151, 0xffff0000, v244
	v_lshlrev_b32_e32 v112, 16, v245
	v_and_b32_e32 v113, 0xffff0000, v245
	v_lshlrev_b32_e32 v152, 16, v246
	v_and_b32_e32 v153, 0xffff0000, v246
	v_lshlrev_b32_e32 v114, 16, v247
	v_and_b32_e32 v115, 0xffff0000, v247
	v_pk_fma_f32 v[64:65], v[64:65], v[108:109], v[112:113]
	v_pk_fma_f32 v[62:63], v[62:63], v[146:147], v[150:151]
	v_pk_fma_f32 v[108:109], v[60:61], v[110:111], v[114:115]
	v_pk_fma_f32 v[60:61], v[58:59], v[148:149], v[152:153]
	v_cvt_pk_bf16_f32 v58, v62, v63
	v_cvt_pk_bf16_f32 v59, v64, v65
	s_waitcnt vmcnt(19)
	v_lshlrev_b32_e32 v62, 16, v184
	v_cvt_pk_bf16_f32 v60, v60, v61
	v_cvt_pk_bf16_f32 v61, v108, v109
	global_store_dwordx4 v[142:143], v[58:61], off
	v_and_b32_e32 v63, 0xffff0000, v184
	v_lshlrev_b32_e32 v64, 16, v185
	v_lshlrev_b32_e32 v58, 16, v182
	v_and_b32_e32 v59, 0xffff0000, v182
	v_and_b32_e32 v65, 0xffff0000, v185
	s_waitcnt vmcnt(19)
	v_lshlrev_b32_e32 v108, 16, v178
	v_and_b32_e32 v109, 0xffff0000, v178
	v_lshlrev_b32_e32 v112, 16, v180
	v_and_b32_e32 v113, 0xffff0000, v180
	v_lshlrev_b32_e32 v114, 16, v181
	v_and_b32_e32 v115, 0xffff0000, v181
	v_lshlrev_b32_e32 v60, 16, v183
	v_and_b32_e32 v61, 0xffff0000, v183
	v_lshlrev_b32_e32 v110, 16, v179
	v_and_b32_e32 v111, 0xffff0000, v179
	v_pk_fma_f32 v[54:55], v[54:55], v[58:59], v[108:109]
	v_pk_fma_f32 v[58:59], v[52:53], v[64:65], v[114:115]
	v_pk_fma_f32 v[52:53], v[50:51], v[62:63], v[112:113]
	v_pk_fma_f32 v[56:57], v[56:57], v[60:61], v[110:111]
	v_cvt_pk_bf16_f32 v50, v54, v55
	s_waitcnt vmcnt(17)
	v_lshlrev_b32_e32 v54, 16, v172
	v_cvt_pk_bf16_f32 v51, v56, v57
	v_cvt_pk_bf16_f32 v52, v52, v53
	v_cvt_pk_bf16_f32 v53, v58, v59
	global_store_dwordx4 v[140:141], v[50:53], off offset:256
	v_and_b32_e32 v55, 0xffff0000, v172
	v_lshlrev_b32_e32 v56, 16, v173
	v_lshlrev_b32_e32 v50, 16, v170
	v_and_b32_e32 v51, 0xffff0000, v170
	v_lshlrev_b32_e32 v52, 16, v171
	v_and_b32_e32 v53, 0xffff0000, v171
	v_and_b32_e32 v57, 0xffff0000, v173
	s_waitcnt vmcnt(17)
	v_lshlrev_b32_e32 v58, 16, v174
	v_and_b32_e32 v59, 0xffff0000, v174
	v_lshlrev_b32_e32 v60, 16, v175
	v_and_b32_e32 v61, 0xffff0000, v175
	v_lshlrev_b32_e32 v62, 16, v176
	v_and_b32_e32 v63, 0xffff0000, v176
	v_lshlrev_b32_e32 v64, 16, v177
	v_and_b32_e32 v65, 0xffff0000, v177
	v_pk_fma_f32 v[48:49], v[48:49], v[52:53], v[60:61]
	v_pk_fma_f32 v[46:47], v[46:47], v[50:51], v[58:59]
	v_pk_fma_f32 v[50:51], v[44:45], v[56:57], v[64:65]
	v_pk_fma_f32 v[44:45], v[42:43], v[54:55], v[62:63]
	v_cvt_pk_bf16_f32 v42, v46, v47
	v_cvt_pk_bf16_f32 v43, v48, v49
	s_waitcnt vmcnt(15)
; __device__ __forceinline__ u32x4 pack8(const f32x4 v0, const f32x4 v1) { u32x4 w; w.x = cvt_pk_bf16(v0[0], v0[1]); w.y = cvt_pk_bf16(v0[2], v0[3]); w.z = cvt_pk_bf16(v1[0], v1[1]); w.w = cvt_pk_bf16(v1[2], v1[3]); return w; }
;     __device__ __forceinline__ void operator()(const f32x4 (&acc)[2][2][4][2], const Unit& u, int wr, int wc, int fr_, int fq) const {
;     ...
;             for (int m = 0; m < 4; ++m)
; #pragma unroll
;                 for (int bj = 0; bj < 2; ++bj) { const size_t r = row0 + ai * HALF + m * 16; const int c = col0 + bj * HALF;
;                     f32x4 g0, g1; unpack8(gw[m][bj], g0, g1);
;                     f32x4 v0 = g0 * acc[ai][bj][m][0], v1 = g1 * acc[ai][bj][m][1];
;                     if (!FIRST) { f32x4 o0, o1; unpack8(ow[m][bj], o0, o1); v0 += o0; v1 += o1; }
;                     *(u32x4*)((Mdst ? Mdst : Mo) + r * DM + c) = pack8(v0, v1); }
;             asm volatile("" ::: "memory"); }
	v_lshlrev_b32_e32 v46, 16, v168
	v_cvt_pk_bf16_f32 v44, v44, v45
	v_cvt_pk_bf16_f32 v45, v50, v51
	global_store_dwordx4 v[144:145], v[42:45], off
	v_and_b32_e32 v47, 0xffff0000, v168
	v_lshlrev_b32_e32 v48, 16, v169
	v_lshlrev_b32_e32 v42, 16, v166
	v_and_b32_e32 v43, 0xffff0000, v166
	v_and_b32_e32 v49, 0xffff0000, v169
	s_waitcnt vmcnt(15)
	v_lshlrev_b32_e32 v50, 16, v162
	v_and_b32_e32 v51, 0xffff0000, v162
	v_lshlrev_b32_e32 v54, 16, v164
	v_and_b32_e32 v55, 0xffff0000, v164
	v_lshlrev_b32_e32 v56, 16, v165
	v_and_b32_e32 v57, 0xffff0000, v165
	v_lshlrev_b32_e32 v44, 16, v167
	v_and_b32_e32 v45, 0xffff0000, v167
	v_lshlrev_b32_e32 v52, 16, v163
	v_and_b32_e32 v53, 0xffff0000, v163
	v_pk_fma_f32 v[38:39], v[38:39], v[42:43], v[50:51]
	v_pk_fma_f32 v[42:43], v[36:37], v[48:49], v[56:57]
	v_pk_fma_f32 v[36:37], v[34:35], v[46:47], v[54:55]
	v_pk_fma_f32 v[40:41], v[40:41], v[44:45], v[52:53]
	v_cvt_pk_bf16_f32 v34, v38, v39
	s_waitcnt vmcnt(13)
	v_lshlrev_b32_e32 v38, 16, v156
	v_cvt_pk_bf16_f32 v35, v40, v41
	v_cvt_pk_bf16_f32 v36, v36, v37
	v_cvt_pk_bf16_f32 v37, v42, v43
	global_store_dwordx4 v[106:107], v[34:37], off offset:256
	v_and_b32_e32 v39, 0xffff0000, v156
	v_lshlrev_b32_e32 v40, 16, v157
	v_lshlrev_b32_e32 v34, 16, v154
	v_and_b32_e32 v35, 0xffff0000, v154
	v_lshlrev_b32_e32 v36, 16, v155
	v_and_b32_e32 v37, 0xffff0000, v155
	v_and_b32_e32 v41, 0xffff0000, v157
	s_waitcnt vmcnt(13)
	v_lshlrev_b32_e32 v42, 16, v158
	v_and_b32_e32 v43, 0xffff0000, v158
	v_lshlrev_b32_e32 v44, 16, v159
	v_and_b32_e32 v45, 0xffff0000, v159
	v_lshlrev_b32_e32 v46, 16, v160
	v_and_b32_e32 v47, 0xffff0000, v160
	v_lshlrev_b32_e32 v48, 16, v161
	v_and_b32_e32 v49, 0xffff0000, v161
	v_pk_fma_f32 v[32:33], v[32:33], v[36:37], v[44:45]
	v_pk_fma_f32 v[30:31], v[30:31], v[34:35], v[42:43]
	v_pk_fma_f32 v[34:35], v[28:29], v[40:41], v[48:49]
	v_pk_fma_f32 v[28:29], v[26:27], v[38:39], v[46:47]
	v_cvt_pk_bf16_f32 v26, v30, v31
	v_cvt_pk_bf16_f32 v27, v32, v33
	s_waitcnt vmcnt(11)
	v_lshlrev_b32_e32 v30, 16, v118
	v_cvt_pk_bf16_f32 v28, v28, v29
	v_cvt_pk_bf16_f32 v29, v34, v35
	global_store_dwordx4 v[104:105], v[26:29], off
	v_and_b32_e32 v31, 0xffff0000, v118
	v_lshlrev_b32_e32 v32, 16, v119
	v_lshlrev_b32_e32 v26, 16, v116
	v_and_b32_e32 v27, 0xffff0000, v116
	v_and_b32_e32 v33, 0xffff0000, v119
	s_waitcnt vmcnt(11)
	v_lshlrev_b32_e32 v34, 16, v120
	v_and_b32_e32 v35, 0xffff0000, v120
	v_lshlrev_b32_e32 v38, 16, v122
	v_and_b32_e32 v39, 0xffff0000, v122
	v_lshlrev_b32_e32 v40, 16, v123
	v_and_b32_e32 v41, 0xffff0000, v123
	v_lshlrev_b32_e32 v28, 16, v117
	v_and_b32_e32 v29, 0xffff0000, v117
	v_lshlrev_b32_e32 v36, 16, v121
	v_and_b32_e32 v37, 0xffff0000, v121
	v_pk_fma_f32 v[22:23], v[22:23], v[26:27], v[34:35]
	v_pk_fma_f32 v[26:27], v[20:21], v[32:33], v[40:41]
	v_pk_fma_f32 v[20:21], v[18:19], v[30:31], v[38:39]
	v_pk_fma_f32 v[24:25], v[24:25], v[28:29], v[36:37]
	v_cvt_pk_bf16_f32 v18, v22, v23
	s_waitcnt vmcnt(9)
	v_lshlrev_b32_e32 v22, 16, v214
	v_cvt_pk_bf16_f32 v19, v24, v25
	v_cvt_pk_bf16_f32 v20, v20, v21
	v_cvt_pk_bf16_f32 v21, v26, v27
	global_store_dwordx4 v[102:103], v[18:21], off offset:256
	v_and_b32_e32 v23, 0xffff0000, v214
	v_lshlrev_b32_e32 v24, 16, v215
	v_lshlrev_b32_e32 v18, 16, v212
	v_and_b32_e32 v19, 0xffff0000, v212
	v_lshlrev_b32_e32 v20, 16, v213
	v_and_b32_e32 v21, 0xffff0000, v213
	v_and_b32_e32 v25, 0xffff0000, v215
	s_waitcnt vmcnt(9)
	v_lshlrev_b32_e32 v26, 16, v216
	v_and_b32_e32 v27, 0xffff0000, v216
	v_lshlrev_b32_e32 v28, 16, v217
	v_and_b32_e32 v29, 0xffff0000, v217
	v_lshlrev_b32_e32 v30, 16, v218
	v_and_b32_e32 v31, 0xffff0000, v218
	v_lshlrev_b32_e32 v32, 16, v219
	v_and_b32_e32 v33, 0xffff0000, v219
	v_pk_fma_f32 v[16:17], v[16:17], v[20:21], v[28:29]
	v_pk_fma_f32 v[14:15], v[14:15], v[18:19], v[26:27]
	v_pk_fma_f32 v[18:19], v[12:13], v[24:25], v[32:33]
	v_pk_fma_f32 v[12:13], v[10:11], v[22:23], v[30:31]
	v_cvt_pk_bf16_f32 v10, v14, v15
	v_cvt_pk_bf16_f32 v11, v16, v17
	s_waitcnt vmcnt(7)
	v_lshlrev_b32_e32 v14, 16, v136
	v_cvt_pk_bf16_f32 v12, v12, v13
	v_cvt_pk_bf16_f32 v13, v18, v19
	global_store_dwordx4 v[100:101], v[10:13], off
	v_and_b32_e32 v15, 0xffff0000, v136
	v_lshlrev_b32_e32 v16, 16, v137
	v_lshlrev_b32_e32 v10, 16, v134
	v_and_b32_e32 v11, 0xffff0000, v134
	v_and_b32_e32 v17, 0xffff0000, v137
	s_waitcnt vmcnt(7)
	v_lshlrev_b32_e32 v18, 16, v130
	v_and_b32_e32 v19, 0xffff0000, v130
	v_lshlrev_b32_e32 v22, 16, v132
	v_and_b32_e32 v23, 0xffff0000, v132
	v_lshlrev_b32_e32 v24, 16, v133
	v_and_b32_e32 v25, 0xffff0000, v133
	v_lshlrev_b32_e32 v12, 16, v135
	v_and_b32_e32 v13, 0xffff0000, v135
	v_lshlrev_b32_e32 v20, 16, v131
	v_and_b32_e32 v21, 0xffff0000, v131
	v_pk_fma_f32 v[6:7], v[6:7], v[10:11], v[18:19]
	v_pk_fma_f32 v[10:11], v[4:5], v[16:17], v[24:25]
	v_pk_fma_f32 v[4:5], v[2:3], v[14:15], v[22:23]
	v_pk_fma_f32 v[8:9], v[8:9], v[12:13], v[20:21]
	v_cvt_pk_bf16_f32 v2, v6, v7
	s_nop 0
	v_cvt_pk_bf16_f32 v3, v8, v9
	v_cvt_pk_bf16_f32 v4, v4, v5
	v_cvt_pk_bf16_f32 v5, v10, v11
	global_store_dwordx4 v[98:99], v[2:5], off offset:256
	s_cbranch_vccnz .LBB0_1156
	s_andn2_b64 vcc, exec, s[8:9]
	s_cbranch_vccnz .LBB0_1155
	s_barrier
	s_branch .LBB0_1155
